# zero accumulators with v_mov_b64 (64 instead of 128 moves per GEMM unit)
# speedup vs baseline: 1.0013x; 1.0013x over previous
; template <class Epi, class Sched, bool ALIGN_EPI = true>
; __device__ __forceinline__ void gemm_phase(PG8_LAS unsigned char* lds, const Gemm g, const Sched& S, const Epi& E, const int tid) {
;     ...
;         const char* nA = has_next ? (const char*)g.A + (size_t)nxt.pm * tstepA + (size_t)nxt.grp * g.gsA + (size_t)nxt.kt0 * kstep : cA;
;         const char* nB = has_next ? (const char*)g.Bt + (size_t)nxt.pn * tstepB + (size_t)nxt.grp * g.gsB + (size_t)nxt.kt0 * kstep : cB;
;     ...
; #pragma unroll
;         for (int a = 0; a < 2; ++a)
; #pragma unroll
;             for (int b = 0; b < 2; ++b)
; #pragma unroll
;                 for (int m = 0; m < 4; ++m)
; #pragma unroll
;                     for (int n = 0; n < 2; ++n) acc[a][b][m][n] = (f32x4){0.f, 0.f, 0.f, 0.f};
;         cur = nxt; cA = nA; cB = nB; ++ui;
.LBB0_425:
	s_ashr_i32 s53, s52, 31
	s_lshl_b64 s[8:9], s[52:53], 20
	s_add_u32 s1, s19, s8
	s_addc_u32 s5, s64, s9
	s_ashr_i32 s55, s54, 31
	s_lshl_b64 s[8:9], s[54:55], 10
	s_add_u32 s58, s1, s8
	s_addc_u32 s59, s5, s9
	s_and_b64 s[8:9], s[38:39], exec
	s_cselect_b32 s1, s59, s63
	s_cselect_b32 s5, s58, s62
	s_ashr_i32 s57, s56, 31
	s_lshl_b64 s[8:9], s[56:57], 18
	s_add_u32 s12, s65, s8
	s_addc_u32 s13, s66, s9
	s_lshl_b64 s[8:9], s[54:55], 19
	s_add_u32 s60, s12, s8
	s_addc_u32 s61, s13, s9
	s_and_b64 s[8:9], s[38:39], exec
	s_cselect_b32 s8, s61, s23
	s_cselect_b32 s9, s60, s22
	s_add_u32 s12, s62, 0x80080
	s_addc_u32 s13, s63, 0
	s_add_u32 s20, s22, 0x100
	v_mov_b32_e32 v4, 0
	s_addc_u32 s21, s23, 0
	s_mov_b32 s53, -2
	v_mov_b32_e32 v5, v4
	v_mov_b64_e32 v[6:7], v[4:5]
	v_mov_b64_e32 v[8:9], v[4:5]
	v_mov_b64_e32 v[10:11], v[4:5]
	v_mov_b64_e32 v[20:21], v[4:5]
	v_mov_b64_e32 v[22:23], v[4:5]
	v_mov_b64_e32 v[24:25], v[4:5]
	v_mov_b64_e32 v[26:27], v[4:5]
	v_mov_b64_e32 v[36:37], v[4:5]
	v_mov_b64_e32 v[38:39], v[4:5]
	v_mov_b64_e32 v[40:41], v[4:5]
	v_mov_b64_e32 v[42:43], v[4:5]
	v_mov_b64_e32 v[52:53], v[4:5]
	v_mov_b64_e32 v[54:55], v[4:5]
	s_waitcnt vmcnt(0)
	v_mov_b64_e32 v[56:57], v[4:5]
	v_mov_b64_e32 v[58:59], v[4:5]
	v_mov_b64_e32 v[12:13], v[4:5]
	v_mov_b64_e32 v[14:15], v[4:5]
	v_mov_b64_e32 v[16:17], v[4:5]
	v_mov_b64_e32 v[18:19], v[4:5]
	v_mov_b64_e32 v[28:29], v[4:5]
	v_mov_b64_e32 v[30:31], v[4:5]
	v_mov_b64_e32 v[32:33], v[4:5]
	v_mov_b64_e32 v[34:35], v[4:5]
	v_mov_b64_e32 v[44:45], v[4:5]
	v_mov_b64_e32 v[46:47], v[4:5]
	v_mov_b64_e32 v[48:49], v[4:5]
	v_mov_b64_e32 v[50:51], v[4:5]
	v_mov_b64_e32 v[76:77], v[4:5]
	v_mov_b64_e32 v[78:79], v[4:5]
	v_mov_b64_e32 v[80:81], v[4:5]
	v_mov_b64_e32 v[82:83], v[4:5]
	v_mov_b64_e32 v[84:85], v[4:5]
	v_mov_b64_e32 v[86:87], v[4:5]
	v_mov_b64_e32 v[88:89], v[4:5]
	v_mov_b64_e32 v[90:91], v[4:5]
	v_mov_b64_e32 v[104:105], v[4:5]
	v_mov_b64_e32 v[106:107], v[4:5]
	v_mov_b64_e32 v[108:109], v[4:5]
	v_mov_b64_e32 v[110:111], v[4:5]
	v_mov_b64_e32 v[128:129], v[4:5]
	v_mov_b64_e32 v[130:131], v[4:5]
	v_mov_b64_e32 v[132:133], v[4:5]
	v_mov_b64_e32 v[134:135], v[4:5]
	v_mov_b64_e32 v[160:161], v[4:5]
	v_mov_b64_e32 v[162:163], v[4:5]
	v_mov_b64_e32 v[164:165], v[4:5]
	v_mov_b64_e32 v[166:167], v[4:5]
	v_mov_b64_e32 v[92:93], v[4:5]
	v_mov_b64_e32 v[94:95], v[4:5]
	v_mov_b64_e32 v[96:97], v[4:5]
	v_mov_b64_e32 v[98:99], v[4:5]
	v_mov_b64_e32 v[120:121], v[4:5]
	v_mov_b64_e32 v[122:123], v[4:5]
	v_mov_b64_e32 v[124:125], v[4:5]
	v_mov_b64_e32 v[126:127], v[4:5]
	v_mov_b64_e32 v[144:145], v[4:5]
	v_mov_b64_e32 v[146:147], v[4:5]
	v_mov_b64_e32 v[148:149], v[4:5]
	v_mov_b64_e32 v[150:151], v[4:5]
	v_mov_b64_e32 v[176:177], v[4:5]
	v_mov_b64_e32 v[178:179], v[4:5]
	v_mov_b64_e32 v[180:181], v[4:5]
	v_mov_b64_e32 v[182:183], v[4:5]

; template <class Epi, class Sched, bool ALIGN_EPI = true>
; __device__ __forceinline__ void gemm_phase(PG8_LAS unsigned char* lds, const Gemm g, const Sched& S, const Epi& E, const int tid) {
;     ...
;         const bool has_next = S.next(ui + 1, nxt);
;         const char* nA = has_next ? (const char*)g.A + (size_t)nxt.pm * tstepA + (size_t)nxt.grp * g.gsA + (size_t)nxt.kt0 * kstep : cA;
;         const char* nB = has_next ? (const char*)g.Bt + (size_t)nxt.pn * tstepB + (size_t)nxt.grp * g.gsB + (size_t)nxt.kt0 * kstep : cB;
;     ...
; #pragma unroll
;         for (int a = 0; a < 2; ++a)
; #pragma unroll
;             for (int b = 0; b < 2; ++b)
; #pragma unroll
;                 for (int m = 0; m < 4; ++m)
; #pragma unroll
;                     for (int n = 0; n < 2; ++n) acc[a][b][m][n] = (f32x4){0.f, 0.f, 0.f, 0.f};
;         cur = nxt; cA = nA; cB = nB; ++ui;
.LBB0_513:
	v_mov_b64_e32 v[4:5], 0x6a4
	s_ashr_i32 s13, s12, 31
	v_cmp_lt_i64_e32 vcc, s[38:39], v[4:5]
	s_lshl_b64 s[38:39], s[12:13], 20
	s_add_u32 s38, s9, s38
	s_addc_u32 s39, s18, s39
	s_and_b64 s[40:41], vcc, exec
	s_cselect_b32 s13, s39, s43
	s_cselect_b32 s52, s38, s42
	s_ashr_i32 s23, s22, 31
	s_lshl_b64 s[40:41], s[22:23], 20
	s_add_u32 s40, s19, s40
	s_addc_u32 s41, s20, s41
	s_and_b64 s[46:47], vcc, exec
	s_cselect_b32 s23, s41, s45
	s_cselect_b32 s53, s40, s44
	s_add_u32 s42, s42, 0x80080
	s_addc_u32 s43, s43, 0
	s_add_u32 s54, s44, 0x100
	v_mov_b32_e32 v4, 0
	s_addc_u32 s55, s45, 0
	s_mov_b32 s56, -2
	v_mov_b32_e32 v5, v4
	v_mov_b64_e32 v[6:7], v[4:5]
	v_mov_b64_e32 v[8:9], v[4:5]
	v_mov_b64_e32 v[10:11], v[4:5]
	v_mov_b64_e32 v[12:13], v[4:5]
	v_mov_b64_e32 v[14:15], v[4:5]
	v_mov_b64_e32 v[20:21], v[4:5]
	v_mov_b64_e32 v[22:23], v[4:5]
	v_mov_b64_e32 v[28:29], v[4:5]
	v_mov_b64_e32 v[30:31], v[4:5]
	v_mov_b64_e32 v[36:37], v[4:5]
	v_mov_b64_e32 v[38:39], v[4:5]
	v_mov_b64_e32 v[44:45], v[4:5]
	v_mov_b64_e32 v[46:47], v[4:5]
	v_mov_b64_e32 v[52:53], v[4:5]
	v_mov_b64_e32 v[54:55], v[4:5]
	v_mov_b64_e32 v[16:17], v[4:5]
	v_mov_b64_e32 v[18:19], v[4:5]
	v_mov_b64_e32 v[24:25], v[4:5]
	v_mov_b64_e32 v[26:27], v[4:5]
	v_mov_b64_e32 v[32:33], v[4:5]
	v_mov_b64_e32 v[34:35], v[4:5]
	v_mov_b64_e32 v[40:41], v[4:5]
	v_mov_b64_e32 v[42:43], v[4:5]
	v_mov_b64_e32 v[48:49], v[4:5]
	v_mov_b64_e32 v[50:51], v[4:5]
	v_mov_b64_e32 v[56:57], v[4:5]
	v_mov_b64_e32 v[58:59], v[4:5]
	v_mov_b64_e32 v[60:61], v[4:5]
	v_mov_b64_e32 v[62:63], v[4:5]
	v_mov_b64_e32 v[64:65], v[4:5]
	v_mov_b64_e32 v[66:67], v[4:5]
	v_mov_b64_e32 v[68:69], v[4:5]
	v_mov_b64_e32 v[70:71], v[4:5]
	v_mov_b64_e32 v[72:73], v[4:5]
	v_mov_b64_e32 v[74:75], v[4:5]
	v_mov_b64_e32 v[76:77], v[4:5]
	v_mov_b64_e32 v[78:79], v[4:5]
	v_mov_b64_e32 v[84:85], v[4:5]
	v_mov_b64_e32 v[86:87], v[4:5]
	v_mov_b64_e32 v[92:93], v[4:5]
	v_mov_b64_e32 v[94:95], v[4:5]
	v_mov_b64_e32 v[100:101], v[4:5]
	v_mov_b64_e32 v[102:103], v[4:5]
	v_mov_b64_e32 v[108:109], v[4:5]
	v_mov_b64_e32 v[110:111], v[4:5]
	v_mov_b64_e32 v[116:117], v[4:5]
	v_mov_b64_e32 v[118:119], v[4:5]
	v_mov_b64_e32 v[80:81], v[4:5]
	v_mov_b64_e32 v[82:83], v[4:5]
	v_mov_b64_e32 v[88:89], v[4:5]
	v_mov_b64_e32 v[90:91], v[4:5]
	v_mov_b64_e32 v[96:97], v[4:5]
	v_mov_b64_e32 v[98:99], v[4:5]
	v_mov_b64_e32 v[104:105], v[4:5]
	v_mov_b64_e32 v[106:107], v[4:5]
	v_mov_b64_e32 v[112:113], v[4:5]
	v_mov_b64_e32 v[114:115], v[4:5]
	v_mov_b64_e32 v[120:121], v[4:5]
	v_mov_b64_e32 v[122:123], v[4:5]
	v_mov_b64_e32 v[124:125], v[4:5]
	v_mov_b64_e32 v[126:127], v[4:5]
	v_mov_b64_e32 v[128:129], v[4:5]
	v_mov_b64_e32 v[130:131], v[4:5]

; template <class Epi, class Sched, bool ALIGN_EPI = true>
; __device__ __forceinline__ void gemm_phase(PG8_LAS unsigned char* lds, const Gemm g, const Sched& S, const Epi& E, const int tid) {
;     ...
; #pragma unroll
;         for (int a = 0; a < 2; ++a)
; #pragma unroll
;             for (int b = 0; b < 2; ++b)
; #pragma unroll
;                 for (int m = 0; m < 4; ++m)
; #pragma unroll
;                     for (int n = 0; n < 2; ++n) acc[a][b][m][n] = (f32x4){0.f, 0.f, 0.f, 0.f};
;         cur = nxt; cA = nA; cB = nB; ++ui;
.LBB0_1086:
	s_add_i32 s1, s9, -2
	s_add_u32 s12, s12, 0x80080
	s_addc_u32 s13, s13, 0
	s_add_u32 s20, s22, 0x100
	v_mov_b32_e32 v4, 0
	s_addc_u32 s21, s23, 0
	s_mov_b32 s22, 0
	v_mov_b32_e32 v5, v4
	v_mov_b64_e32 v[6:7], v[4:5]
	v_mov_b64_e32 v[8:9], v[4:5]
	v_mov_b64_e32 v[10:11], v[4:5]
	v_mov_b64_e32 v[20:21], v[4:5]
	v_mov_b64_e32 v[22:23], v[4:5]
	v_mov_b64_e32 v[24:25], v[4:5]
	v_mov_b64_e32 v[26:27], v[4:5]
	v_mov_b64_e32 v[36:37], v[4:5]
	v_mov_b64_e32 v[38:39], v[4:5]
	v_mov_b64_e32 v[40:41], v[4:5]
	v_mov_b64_e32 v[42:43], v[4:5]
	v_mov_b64_e32 v[52:53], v[4:5]
	v_mov_b64_e32 v[54:55], v[4:5]
	s_waitcnt vmcnt(0)
	v_mov_b64_e32 v[60:61], v[4:5]
	v_mov_b64_e32 v[62:63], v[4:5]
	v_mov_b64_e32 v[12:13], v[4:5]
	v_mov_b64_e32 v[14:15], v[4:5]
	v_mov_b64_e32 v[16:17], v[4:5]
	v_mov_b64_e32 v[18:19], v[4:5]
	v_mov_b64_e32 v[28:29], v[4:5]
	v_mov_b64_e32 v[30:31], v[4:5]
	v_mov_b64_e32 v[32:33], v[4:5]
	v_mov_b64_e32 v[34:35], v[4:5]
	v_mov_b64_e32 v[44:45], v[4:5]
	v_mov_b64_e32 v[46:47], v[4:5]
	v_mov_b64_e32 v[48:49], v[4:5]
	v_mov_b64_e32 v[50:51], v[4:5]
	v_mov_b64_e32 v[76:77], v[4:5]
	v_mov_b64_e32 v[78:79], v[4:5]
	v_mov_b64_e32 v[80:81], v[4:5]
	v_mov_b64_e32 v[82:83], v[4:5]
	v_mov_b64_e32 v[84:85], v[4:5]
	v_mov_b64_e32 v[86:87], v[4:5]
	v_mov_b64_e32 v[88:89], v[4:5]
	v_mov_b64_e32 v[90:91], v[4:5]
	v_mov_b64_e32 v[108:109], v[4:5]
	v_mov_b64_e32 v[110:111], v[4:5]
	v_mov_b64_e32 v[112:113], v[4:5]
	v_mov_b64_e32 v[114:115], v[4:5]
	v_mov_b64_e32 v[132:133], v[4:5]
	v_mov_b64_e32 v[134:135], v[4:5]
	v_mov_b64_e32 v[136:137], v[4:5]
	v_mov_b64_e32 v[138:139], v[4:5]
	v_mov_b64_e32 v[164:165], v[4:5]
	v_mov_b64_e32 v[166:167], v[4:5]
	v_mov_b64_e32 v[168:169], v[4:5]
	v_mov_b64_e32 v[170:171], v[4:5]
	v_mov_b64_e32 v[96:97], v[4:5]
	v_mov_b64_e32 v[98:99], v[4:5]
	v_mov_b64_e32 v[100:101], v[4:5]
	v_mov_b64_e32 v[102:103], v[4:5]
	v_mov_b64_e32 v[120:121], v[4:5]
	v_mov_b64_e32 v[122:123], v[4:5]
	v_mov_b64_e32 v[124:125], v[4:5]
	v_mov_b64_e32 v[126:127], v[4:5]
	v_mov_b64_e32 v[144:145], v[4:5]
	v_mov_b64_e32 v[146:147], v[4:5]
	v_mov_b64_e32 v[148:149], v[4:5]
	v_mov_b64_e32 v[150:151], v[4:5]
	v_mov_b64_e32 v[176:177], v[4:5]
	v_mov_b64_e32 v[178:179], v[4:5]
	v_mov_b64_e32 v[180:181], v[4:5]
	v_mov_b64_e32 v[182:183], v[4:5]

; template <class Epi, class Sched, bool ALIGN_EPI = true>
; __device__ __forceinline__ void gemm_phase(PG8_LAS unsigned char* lds, const Gemm g, const Sched& S, const Epi& E, const int tid) {
;     ...
;         const char* nA = has_next ? (const char*)g.A + (size_t)nxt.pm * tstepA + (size_t)nxt.grp * g.gsA + (size_t)nxt.kt0 * kstep : cA;
;         const char* nB = has_next ? (const char*)g.Bt + (size_t)nxt.pn * tstepB + (size_t)nxt.grp * g.gsB + (size_t)nxt.kt0 * kstep : cB;
;     ...
; #pragma unroll
;         for (int a = 0; a < 2; ++a)
; #pragma unroll
;             for (int b = 0; b < 2; ++b)
; #pragma unroll
;                 for (int m = 0; m < 4; ++m)
; #pragma unroll
;                     for (int n = 0; n < 2; ++n) acc[a][b][m][n] = (f32x4){0.f, 0.f, 0.f, 0.f};
;         cur = nxt; cA = nA; cB = nB; ++ui;
.LBB0_1237:
	s_ashr_i32 s13, s12, 31
	s_lshl_b64 s[0:1], s[12:13], 20
	s_add_u32 s0, s81, s0
	s_addc_u32 s1, s82, s1
	s_and_b64 s[18:19], s[50:51], exec
	s_cselect_b32 s8, s1, s75
	s_cselect_b32 s11, s0, s74
	s_ashr_i32 s23, s22, 31
	s_lshl_b64 s[18:19], s[22:23], 20
	s_add_u32 s70, s83, s18
	s_addc_u32 s71, s84, s19
	s_and_b64 s[18:19], s[50:51], exec
	s_cselect_b32 s13, s71, s77
	s_cselect_b32 s18, s70, s76
	s_add_u32 s74, s74, 0x80080
	s_addc_u32 s75, s75, 0
	s_add_u32 s19, s76, 0x100
	v_mov_b32_e32 v12, 0
	s_addc_u32 s20, s77, 0
	s_mov_b32 s21, -2
	v_mov_b32_e32 v13, v12
	v_mov_b64_e32 v[14:15], v[12:13]
	v_mov_b64_e32 v[16:17], v[12:13]
	v_mov_b64_e32 v[18:19], v[12:13]
	v_mov_b64_e32 v[20:21], v[12:13]
	v_mov_b64_e32 v[22:23], v[12:13]
	v_mov_b64_e32 v[24:25], v[12:13]
	v_mov_b64_e32 v[26:27], v[12:13]
	v_mov_b64_e32 v[36:37], v[12:13]
	v_mov_b64_e32 v[38:39], v[12:13]
	v_mov_b64_e32 v[40:41], v[12:13]
	v_mov_b64_e32 v[42:43], v[12:13]
	v_mov_b64_e32 v[52:53], v[12:13]
	v_mov_b64_e32 v[54:55], v[12:13]
	s_waitcnt vmcnt(0)
	v_mov_b64_e32 v[56:57], v[12:13]
	v_mov_b64_e32 v[58:59], v[12:13]
	v_mov_b64_e32 v[4:5], v[12:13]
	v_mov_b64_e32 v[6:7], v[12:13]
	v_mov_b64_e32 v[8:9], v[12:13]
	v_mov_b64_e32 v[10:11], v[12:13]
	v_mov_b64_e32 v[28:29], v[12:13]
	v_mov_b64_e32 v[30:31], v[12:13]
	v_mov_b64_e32 v[32:33], v[12:13]
	v_mov_b64_e32 v[34:35], v[12:13]
	v_mov_b64_e32 v[44:45], v[12:13]
	v_mov_b64_e32 v[46:47], v[12:13]
	v_mov_b64_e32 v[48:49], v[12:13]
	v_mov_b64_e32 v[50:51], v[12:13]
	v_mov_b64_e32 v[60:61], v[12:13]
	v_mov_b64_e32 v[62:63], v[12:13]
	v_mov_b64_e32 v[64:65], v[12:13]
	v_mov_b64_e32 v[66:67], v[12:13]
	v_mov_b64_e32 v[108:109], v[12:13]
	v_mov_b64_e32 v[110:111], v[12:13]
	v_mov_b64_e32 v[112:113], v[12:13]
	v_mov_b64_e32 v[114:115], v[12:13]
	v_mov_b64_e32 v[116:117], v[12:13]
	v_mov_b64_e32 v[118:119], v[12:13]
	v_mov_b64_e32 v[120:121], v[12:13]
	v_mov_b64_e32 v[122:123], v[12:13]
	v_mov_b64_e32 v[132:133], v[12:13]
	v_mov_b64_e32 v[134:135], v[12:13]
	v_mov_b64_e32 v[136:137], v[12:13]
	v_mov_b64_e32 v[138:139], v[12:13]
	v_mov_b64_e32 v[148:149], v[12:13]
	v_mov_b64_e32 v[150:151], v[12:13]
	v_mov_b64_e32 v[152:153], v[12:13]
	v_mov_b64_e32 v[154:155], v[12:13]
	v_mov_b64_e32 v[68:69], v[12:13]
	v_mov_b64_e32 v[70:71], v[12:13]
	v_mov_b64_e32 v[80:81], v[12:13]
	v_mov_b64_e32 v[82:83], v[12:13]
	v_mov_b64_e32 v[124:125], v[12:13]
	v_mov_b64_e32 v[126:127], v[12:13]
	v_mov_b64_e32 v[128:129], v[12:13]
	v_mov_b64_e32 v[130:131], v[12:13]
	v_mov_b64_e32 v[140:141], v[12:13]
	v_mov_b64_e32 v[142:143], v[12:13]
	v_mov_b64_e32 v[144:145], v[12:13]
	v_mov_b64_e32 v[146:147], v[12:13]
	v_mov_b64_e32 v[156:157], v[12:13]
	v_mov_b64_e32 v[158:159], v[12:13]
	v_mov_b64_e32 v[160:161], v[12:13]
	v_mov_b64_e32 v[162:163], v[12:13]

; template <class Epi, class Sched, bool ALIGN_EPI = true>
; __device__ __forceinline__ void gemm_phase(PG8_LAS unsigned char* lds, const Gemm g, const Sched& S, const Epi& E, const int tid) {
;     ...
; #pragma unroll
;         for (int a = 0; a < 2; ++a)
; #pragma unroll
;             for (int b = 0; b < 2; ++b)
; #pragma unroll
;                 for (int m = 0; m < 4; ++m)
; #pragma unroll
;                     for (int n = 0; n < 2; ++n) acc[a][b][m][n] = (f32x4){0.f, 0.f, 0.f, 0.f};
;         cur = nxt; cA = nA; cB = nB; ++ui;
.LBB0_1413:
	s_add_i32 s45, s67, -2
	s_add_u32 s68, s12, 0x100
	v_mov_b32_e32 v4, 0
	s_addc_u32 s69, s13, 0
	s_mov_b32 s12, 0
	v_mov_b32_e32 v5, v4
	v_mov_b64_e32 v[6:7], v[4:5]
	v_mov_b64_e32 v[8:9], v[4:5]
	v_mov_b64_e32 v[10:11], v[4:5]
	v_mov_b64_e32 v[20:21], v[4:5]
	v_mov_b64_e32 v[22:23], v[4:5]
	v_mov_b64_e32 v[24:25], v[4:5]
	v_mov_b64_e32 v[26:27], v[4:5]
	v_mov_b64_e32 v[36:37], v[4:5]
	v_mov_b64_e32 v[38:39], v[4:5]
	v_mov_b64_e32 v[40:41], v[4:5]
	v_mov_b64_e32 v[42:43], v[4:5]
	v_mov_b64_e32 v[52:53], v[4:5]
	v_mov_b64_e32 v[54:55], v[4:5]
	s_waitcnt vmcnt(0)
	v_mov_b64_e32 v[64:65], v[4:5]
	v_mov_b64_e32 v[66:67], v[4:5]
	v_mov_b64_e32 v[12:13], v[4:5]
	v_mov_b64_e32 v[14:15], v[4:5]
	v_mov_b64_e32 v[16:17], v[4:5]
	v_mov_b64_e32 v[18:19], v[4:5]
	v_mov_b64_e32 v[28:29], v[4:5]
	v_mov_b64_e32 v[30:31], v[4:5]
	v_mov_b64_e32 v[32:33], v[4:5]
	v_mov_b64_e32 v[34:35], v[4:5]
	v_mov_b64_e32 v[44:45], v[4:5]
	v_mov_b64_e32 v[46:47], v[4:5]
	v_mov_b64_e32 v[48:49], v[4:5]
	v_mov_b64_e32 v[50:51], v[4:5]
	v_mov_b64_e32 v[76:77], v[4:5]
	v_mov_b64_e32 v[78:79], v[4:5]
	v_mov_b64_e32 v[80:81], v[4:5]
	v_mov_b64_e32 v[82:83], v[4:5]
	v_mov_b64_e32 v[84:85], v[4:5]
	v_mov_b64_e32 v[86:87], v[4:5]
	v_mov_b64_e32 v[88:89], v[4:5]
	v_mov_b64_e32 v[90:91], v[4:5]
	v_mov_b64_e32 v[108:109], v[4:5]
	v_mov_b64_e32 v[110:111], v[4:5]
	v_mov_b64_e32 v[112:113], v[4:5]
	v_mov_b64_e32 v[114:115], v[4:5]
	v_mov_b64_e32 v[132:133], v[4:5]
	v_mov_b64_e32 v[134:135], v[4:5]
	v_mov_b64_e32 v[136:137], v[4:5]
	v_mov_b64_e32 v[138:139], v[4:5]
	v_mov_b64_e32 v[164:165], v[4:5]
	v_mov_b64_e32 v[166:167], v[4:5]
	v_mov_b64_e32 v[168:169], v[4:5]
	v_mov_b64_e32 v[170:171], v[4:5]
	v_mov_b64_e32 v[96:97], v[4:5]
	v_mov_b64_e32 v[98:99], v[4:5]
	v_mov_b64_e32 v[100:101], v[4:5]
	v_mov_b64_e32 v[102:103], v[4:5]
	v_mov_b64_e32 v[120:121], v[4:5]
	v_mov_b64_e32 v[122:123], v[4:5]
	v_mov_b64_e32 v[124:125], v[4:5]
	v_mov_b64_e32 v[126:127], v[4:5]
	v_mov_b64_e32 v[144:145], v[4:5]
	v_mov_b64_e32 v[146:147], v[4:5]
	v_mov_b64_e32 v[148:149], v[4:5]
	v_mov_b64_e32 v[150:151], v[4:5]
	v_mov_b64_e32 v[176:177], v[4:5]
	v_mov_b64_e32 v[178:179], v[4:5]
	v_mov_b64_e32 v[180:181], v[4:5]
	v_mov_b64_e32 v[182:183], v[4:5]
	s_nop 0
	s_nop 0
	s_nop 0
	s_nop 0
